# x1 no longer stored by P8 row pass and re-read in P12: P12 recomputes it from x,y,rowss1 (hand-written P12 prompt row-pass loop, nt hints kept)
# speedup vs baseline: 1.0134x; 1.0134x over previous
; __device__ __forceinline__ float wave_sum(float v) { for (int o = 32; o >= 1; o >>= 1) v += __shfl_xor(v, o); return v; }
; __device__ __forceinline__ u32x2 pk4(f32x4 v) { u32x2 w; w.x = cvt_pk_bf16(v[0], v[1]); w.y = cvt_pk_bf16(v[2], v[3]); return w; }
; __device__ __forceinline__ f32x4 up4(u32x2 w) { return (f32x4){bf_lo(w.x), bf_hi(w.x), bf_lo(w.y), bf_hi(w.y)}; }
; __device__ __forceinline__ void row_pass1(const Args& a, int row_lo, int row_hi, int gw, int NGW, int lane) {
;     ...
;     for (int r0 = row_lo + 2 * gw; r0 < row_hi; r0 += 2 * NGW) {
;         f32x4 xv[2][4]; u32x2 yv[2][4]; float rs[2];
; #pragma unroll
;         for (int r = 0; r < 2; ++r) { const int row = (r0 + r < row_hi) ? r0 + r : r0; rs[r] = rss[row];
;             const f32x4* xr = (const f32x4*)xrow_ptr(a, row) + lane; const u32x2* yr = (const u32x2*)(Y + (size_t)row * DM) + lane;
; #pragma unroll
;             for (int j = 0; j < 4; ++j) { xv[r][j] = xr[64 * j]; yv[r][j] = yr[64 * j]; } }
; #pragma unroll
;         for (int r = 0; r < 2; ++r) { const int row = r0 + r; if (row >= row_hi) break;
;             const float rstd = rsqrtf(rs[r] * (1.f / DM) + EPS); f32x4 v[4]; float s = 0.f;
; #pragma unroll
;             for (int j = 0; j < 4; ++j) { v[j] = xv[r][j] + up4(yv[r][j]) * rstd * gp[j]; s += (v[j][0] * v[j][0] + v[j][1] * v[j][1]) + (v[j][2] * v[j][2] + v[j][3] * v[j][3]); }
;             const float rstd2 = rsqrtf(wave_sum(s) * (1.f / DM) + EPS);
;             f32x4* xo = (f32x4*)(XO + (size_t)row * DM) + lane; u32x2* ao = (u32x2*)(A2 + (size_t)row * DM) + lane;
; #pragma unroll
;             for (int j = 0; j < 4; ++j) { xo[64 * j] = v[j]; ao[64 * j] = pk4(v[j] * rstd2 * gq[j]); } }
.LBB0_1040:
	s_add_i32 s3, s8, 1
	s_cmpk_lt_i32 s3, 0x4000
	s_cselect_b32 s0, s3, s8
	s_ashr_i32 s1, s0, 31
	s_lshl_b64 s[28:29], s[0:1], 2
	s_add_u32 s28, s6, s28
	s_addc_u32 s29, s7, s29
	s_add_i32 s30, s0, 0xffffc000
	s_cmpk_lt_i32 s0, 0x4000
	v_readlane_b32 s36, v252, 1
	s_cselect_b32 s31, s1, 0
	s_cselect_b32 s30, s0, s30
	v_readlane_b32 s37, v252, 2
	v_readlane_b32 s38, v252, 3
	v_readlane_b32 s39, v252, 4
	s_cselect_b32 s33, s37, s39
	s_cselect_b32 s34, s36, s38
	s_lshl_b64 s[30:31], s[30:31], 12
	s_add_u32 s30, s34, s30
	v_lshl_add_u64 v[88:89], s[54:55], 0, v[50:51]
	s_addc_u32 s31, s33, s31
	s_lshl_b64 s[0:1], s[0:1], 11
	s_waitcnt vmcnt(6)
	v_add_co_u32_e32 v32, vcc, s11, v88
	s_add_u32 s34, s54, s9
	s_nop 0
	v_addc_co_u32_e32 v33, vcc, 0, v89, vcc
	s_addc_u32 s35, s55, s24
	global_load_dwordx2 v[84:85], v[32:33], off offset:1536
	global_load_dwordx2 v[86:87], v[32:33], off offset:1024
	global_load_dwordx2 v[90:91], v[32:33], off offset:512
	global_load_dwordx2 v[92:93], v[32:33], off
	global_load_dword v101, v161, s[34:35]
	v_lshl_add_u64 v[32:33], s[22:23], 0, v[160:161]
	global_load_dwordx4 v[60:63], v[32:33], off
	global_load_dwordx4 v[72:75], v[32:33], off offset:1024
	global_load_dwordx4 v[76:79], v[32:33], off offset:2048
	global_load_dwordx4 v[80:83], v[32:33], off offset:3072
	global_load_dword v71, v161, s[28:29]
	v_lshl_add_u64 v[94:95], v[48:49], 0, s[0:1]
	global_load_dwordx4 v[44:47], v160, s[30:31]
	global_load_dwordx4 v[40:43], v160, s[30:31] offset:1024
	s_waitcnt lgkmcnt(0)
	global_load_dwordx4 v[36:39], v160, s[30:31] offset:2048
	global_load_dwordx4 v[32:35], v160, s[30:31] offset:3072
	global_load_dwordx2 v[58:59], v[94:95], off
	global_load_dwordx2 v[56:57], v[94:95], off offset:512
	global_load_dwordx2 v[54:55], v[94:95], off offset:1024
	global_load_dwordx2 v[52:53], v[94:95], off offset:1536
	s_cmpk_gt_i32 s3, 0x3fff
	v_readlane_b32 s40, v252, 5
	v_readlane_b32 s41, v252, 6
	v_readlane_b32 s42, v252, 7
	v_readlane_b32 s43, v252, 8
	v_readlane_b32 s44, v252, 9
	v_readlane_b32 s45, v252, 10
	v_readlane_b32 s46, v252, 11
	v_readlane_b32 s47, v252, 12
	v_readlane_b32 s48, v252, 13
	v_readlane_b32 s49, v252, 14
	v_readlane_b32 s50, v252, 15
	v_readlane_b32 s51, v252, 16
	s_waitcnt vmcnt(17)
	v_lshlrev_b32_e32 v100, 16, v84
	s_waitcnt vmcnt(16)
	v_lshlrev_b32_e32 v98, 16, v86
	s_waitcnt vmcnt(15)
	v_lshlrev_b32_e32 v96, 16, v90
	s_waitcnt vmcnt(14)
	v_lshlrev_b32_e32 v94, 16, v92
	s_waitcnt vmcnt(13)
	v_fmamk_f32 v101, v101, 0x3a800000, v70
	v_mul_f32_e32 v102, 0x4b800000, v101
	v_cmp_gt_f32_e32 vcc, s25, v101
	v_and_b32_e32 v95, 0xffff0000, v92
	v_lshlrev_b32_e32 v92, 16, v93
	v_cndmask_b32_e32 v101, v101, v102, vcc
	v_rsq_f32_e32 v102, v101
	v_and_b32_e32 v93, 0xffff0000, v93
	v_and_b32_e32 v97, 0xffff0000, v90
	v_lshlrev_b32_e32 v90, 16, v91
	v_mul_f32_e32 v103, 0x45800000, v102
	v_and_b32_e32 v91, 0xffff0000, v91
	v_cndmask_b32_e32 v102, v102, v103, vcc
	v_and_b32_e32 v99, 0xffff0000, v86
	v_lshlrev_b32_e32 v86, 16, v87
	v_and_b32_e32 v87, 0xffff0000, v87
	v_and_b32_e32 v101, 0xffff0000, v84
	v_lshlrev_b32_e32 v84, 16, v85
	v_and_b32_e32 v85, 0xffff0000, v85
	v_pk_mul_f32 v[94:95], v[102:103], v[94:95] op_sel_hi:[0,1]
	v_pk_mul_f32 v[92:93], v[102:103], v[92:93] op_sel_hi:[0,1]
	v_pk_mul_f32 v[96:97], v[102:103], v[96:97] op_sel_hi:[0,1]
	v_pk_mul_f32 v[90:91], v[102:103], v[90:91] op_sel_hi:[0,1]
	v_pk_mul_f32 v[98:99], v[102:103], v[98:99] op_sel_hi:[0,1]
	v_pk_mul_f32 v[104:105], v[102:103], v[86:87] op_sel_hi:[0,1]
	v_pk_mul_f32 v[100:101], v[102:103], v[100:101] op_sel_hi:[0,1]
	v_pk_mul_f32 v[102:103], v[102:103], v[84:85] op_sel_hi:[0,1]
	s_waitcnt vmcnt(12)
	v_pk_fma_f32 v[86:87], v[2:3], v[92:93], v[62:63]
	v_pk_fma_f32 v[84:85], v[0:1], v[94:95], v[60:61]
	s_waitcnt vmcnt(11)
	v_pk_fma_f32 v[74:75], v[10:11], v[90:91], v[74:75]
	v_pk_fma_f32 v[72:73], v[8:9], v[96:97], v[72:73]
	v_pk_mul_f32 v[60:61], v[86:87], v[86:87]
	v_pk_mul_f32 v[62:63], v[84:85], v[84:85]
	v_pk_mul_f32 v[90:91], v[74:75], v[74:75]
	v_pk_mul_f32 v[92:93], v[72:73], v[72:73]
	s_waitcnt vmcnt(10)
	v_pk_fma_f32 v[78:79], v[18:19], v[104:105], v[78:79]
	v_pk_fma_f32 v[76:77], v[16:17], v[98:99], v[76:77]
	v_pk_mov_b32 v[98:99], v[62:63], v[60:61] op_sel:[1,0]
	v_mov_b32_e32 v63, v61
	v_pk_mov_b32 v[60:61], v[92:93], v[90:91] op_sel:[1,0]
	v_mov_b32_e32 v93, v91
	v_mul_f32_e32 v94, v76, v76
	v_mul_f32_e32 v96, v78, v78
	v_pk_add_f32 v[62:63], v[98:99], v[62:63]
	v_pk_add_f32 v[60:61], v[60:61], v[92:93]
	s_waitcnt vmcnt(9)
	v_pk_fma_f32 v[82:83], v[26:27], v[102:103], v[82:83]
	v_pk_fma_f32 v[80:81], v[24:25], v[100:101], v[80:81]
	v_pk_fma_f32 v[90:91], v[76:77], v[76:77], v[94:95] op_sel_hi:[1,1,0]
	v_pk_fma_f32 v[94:95], v[78:79], v[78:79], v[96:97] op_sel_hi:[1,1,0]
	v_pk_add_f32 v[62:63], v[62:63], v[62:63] op_sel_hi:[0,1]
	v_pk_add_f32 v[60:61], v[60:61], v[60:61] op_sel_hi:[0,1]
	v_mul_f32_e32 v90, v80, v80
	v_mul_f32_e32 v94, v81, v81
	v_mul_f32_e32 v62, v82, v82
	v_mul_f32_e32 v60, v83, v83
	v_pk_add_f32 v[90:91], v[90:91], v[94:95]
	v_pk_add_f32 v[60:61], v[62:63], v[60:61]
	v_lshl_add_u64 v[62:63], s[14:15], 0, v[160:161]
	v_pk_add_f32 v[60:61], v[90:91], v[60:61]
	v_add_f32_e32 v60, v60, v61
	ds_bpermute_b32 v61, v64, v60
	s_waitcnt lgkmcnt(0)
	v_add_f32_e32 v60, v60, v61
	ds_bpermute_b32 v61, v65, v60
	s_waitcnt lgkmcnt(0)
	v_add_f32_e32 v60, v60, v61
	ds_bpermute_b32 v61, v66, v60
	s_waitcnt lgkmcnt(0)
	v_add_f32_e32 v60, v60, v61
	ds_bpermute_b32 v61, v67, v60
	s_waitcnt lgkmcnt(0)
	v_add_f32_e32 v60, v60, v61
	ds_bpermute_b32 v61, v68, v60
	s_waitcnt lgkmcnt(0)
	v_add_f32_e32 v60, v60, v61
	ds_bpermute_b32 v61, v69, v60
	s_waitcnt lgkmcnt(0)
; __device__ __forceinline__ float wave_sum(float v) { for (int o = 32; o >= 1; o >>= 1) v += __shfl_xor(v, o); return v; }
; __device__ __forceinline__ u32x2 pk4(f32x4 v) { u32x2 w; w.x = cvt_pk_bf16(v[0], v[1]); w.y = cvt_pk_bf16(v[2], v[3]); return w; }
; __device__ __forceinline__ f32x4 up4(u32x2 w) { return (f32x4){bf_lo(w.x), bf_hi(w.x), bf_lo(w.y), bf_hi(w.y)}; }
; __device__ __forceinline__ void row_pass1(const Args& a, int row_lo, int row_hi, int gw, int NGW, int lane) {
;     ...
;         for (int r = 0; r < 2; ++r) { const int row = r0 + r; if (row >= row_hi) break;
;             const float rstd = rsqrtf(rs[r] * (1.f / DM) + EPS); f32x4 v[4]; float s = 0.f;
; #pragma unroll
;             for (int j = 0; j < 4; ++j) { v[j] = xv[r][j] + up4(yv[r][j]) * rstd * gp[j]; s += (v[j][0] * v[j][0] + v[j][1] * v[j][1]) + (v[j][2] * v[j][2] + v[j][3] * v[j][3]); }
;             const float rstd2 = rsqrtf(wave_sum(s) * (1.f / DM) + EPS);
;             f32x4* xo = (f32x4*)(XO + (size_t)row * DM) + lane; u32x2* ao = (u32x2*)(A2 + (size_t)row * DM) + lane;
; #pragma unroll
;             for (int j = 0; j < 4; ++j) { xo[64 * j] = v[j]; ao[64 * j] = pk4(v[j] * rstd2 * gq[j]); } }
	v_add_f32_e32 v60, v60, v61
	v_fmamk_f32 v60, v60, 0x3a800000, v70
	v_mul_f32_e32 v61, 0x4b800000, v60
	v_cmp_gt_f32_e32 vcc, s25, v60
	s_nop 1
	v_cndmask_b32_e32 v60, v60, v61, vcc
	v_rsq_f32_e32 v90, v60
	v_add_co_u32_e64 v60, s[0:1], s26, v88
	v_mul_f32_e32 v88, 0x45800000, v90
	v_cndmask_b32_e32 v88, v90, v88, vcc
	v_addc_co_u32_e64 v61, s[0:1], 0, v89, s[0:1]
	v_pk_mul_f32 v[84:85], v[84:85], v[88:89] op_sel_hi:[1,0]
	v_pk_mul_f32 v[86:87], v[86:87], v[88:89] op_sel_hi:[1,0]
	v_pk_mul_f32 v[90:91], v[72:73], v[88:89] op_sel_hi:[1,0]
	v_pk_mul_f32 v[92:93], v[74:75], v[88:89] op_sel_hi:[1,0]
	v_pk_mul_f32 v[94:95], v[76:77], v[88:89] op_sel_hi:[1,0]
	v_pk_mul_f32 v[96:97], v[78:79], v[88:89] op_sel_hi:[1,0]
	v_pk_mul_f32 v[98:99], v[80:81], v[88:89] op_sel_hi:[1,0]
	v_pk_mul_f32 v[88:89], v[82:83], v[88:89] op_sel_hi:[1,0]
	v_pk_mul_f32 v[86:87], v[6:7], v[86:87]
	v_pk_mul_f32 v[84:85], v[4:5], v[84:85]
	v_pk_mul_f32 v[92:93], v[14:15], v[92:93]
	v_pk_mul_f32 v[88:89], v[30:31], v[88:89]
	v_pk_mul_f32 v[98:99], v[28:29], v[98:99]
	v_pk_mul_f32 v[90:91], v[12:13], v[90:91]
	v_pk_mul_f32 v[96:97], v[22:23], v[96:97]
	v_pk_mul_f32 v[94:95], v[20:21], v[94:95]
	v_cvt_pk_bf16_f32 v84, v84, v85
	v_cvt_pk_bf16_f32 v85, v86, v87
	v_cvt_pk_bf16_f32 v87, v92, v93
	v_cvt_pk_bf16_f32 v92, v98, v99
	v_cvt_pk_bf16_f32 v93, v88, v89
	v_cvt_pk_bf16_f32 v86, v90, v91
	v_cvt_pk_bf16_f32 v90, v94, v95
	v_cvt_pk_bf16_f32 v91, v96, v97
	global_store_dwordx2 v[60:61], v[84:85], off
	global_store_dwordx2 v[60:61], v[86:87], off offset:512
	global_store_dwordx2 v[60:61], v[90:91], off offset:1024
	global_store_dwordx2 v[60:61], v[92:93], off offset:1536
	s_cbranch_scc1 .LBB0_1039
	s_waitcnt vmcnt(12)
	v_fmamk_f32 v71, v71, 0x3a800000, v70
	v_mul_f32_e32 v72, 0x4b800000, v71
	v_cmp_gt_f32_e32 vcc, s25, v71
	s_waitcnt vmcnt(7)
	v_and_b32_e32 v73, 0xffff0000, v58
	v_lshlrev_b32_e32 v74, 16, v59
	v_cndmask_b32_e32 v71, v71, v72, vcc
	v_rsq_f32_e32 v71, v71
	v_lshlrev_b32_e32 v72, 16, v58
	v_and_b32_e32 v75, 0xffff0000, v59
	v_mul_f32_e32 v58, 0x45800000, v71
	v_cndmask_b32_e32 v58, v71, v58, vcc
	v_pk_mul_f32 v[72:73], v[58:59], v[72:73] op_sel_hi:[0,1]
	v_pk_mul_f32 v[74:75], v[58:59], v[74:75] op_sel_hi:[0,1]
	v_pk_fma_f32 v[46:47], v[2:3], v[74:75], v[46:47]
	v_pk_fma_f32 v[44:45], v[0:1], v[72:73], v[44:45]
	v_pk_mul_f32 v[72:73], v[46:47], v[46:47]
	v_pk_mul_f32 v[74:75], v[44:45], v[44:45]
	s_nop 0
	v_pk_mov_b32 v[76:77], v[74:75], v[72:73] op_sel:[1,0]
	v_mov_b32_e32 v75, v73
	v_pk_add_f32 v[72:73], v[76:77], v[74:75]
	s_waitcnt vmcnt(6)
	v_lshlrev_b32_e32 v74, 16, v56
	v_and_b32_e32 v75, 0xffff0000, v56
	v_lshlrev_b32_e32 v56, 16, v57
	v_and_b32_e32 v57, 0xffff0000, v57
	v_pk_mul_f32 v[74:75], v[58:59], v[74:75] op_sel_hi:[0,1]
	v_pk_mul_f32 v[56:57], v[58:59], v[56:57] op_sel_hi:[0,1]
	v_pk_fma_f32 v[42:43], v[10:11], v[56:57], v[42:43]
	v_pk_fma_f32 v[40:41], v[8:9], v[74:75], v[40:41]
	v_pk_mul_f32 v[56:57], v[42:43], v[42:43]
	v_pk_mul_f32 v[74:75], v[40:41], v[40:41]
	s_nop 0
	v_pk_mov_b32 v[76:77], v[74:75], v[56:57] op_sel:[1,0]
	v_mov_b32_e32 v75, v57
	v_pk_add_f32 v[56:57], v[76:77], v[74:75]
	s_waitcnt vmcnt(5)
	v_lshlrev_b32_e32 v74, 16, v54
	v_and_b32_e32 v75, 0xffff0000, v54
	v_lshlrev_b32_e32 v54, 16, v55
	v_and_b32_e32 v55, 0xffff0000, v55
	v_pk_mul_f32 v[54:55], v[58:59], v[54:55] op_sel_hi:[0,1]
	v_pk_fma_f32 v[38:39], v[18:19], v[54:55], v[38:39]
	s_waitcnt vmcnt(4)
	v_lshlrev_b32_e32 v54, 16, v52
	v_and_b32_e32 v55, 0xffff0000, v52
	v_lshlrev_b32_e32 v52, 16, v53
	v_and_b32_e32 v53, 0xffff0000, v53
	v_pk_mul_f32 v[54:55], v[58:59], v[54:55] op_sel_hi:[0,1]
	v_pk_mul_f32 v[52:53], v[58:59], v[52:53] op_sel_hi:[0,1]
	v_pk_fma_f32 v[32:33], v[24:25], v[54:55], v[32:33]
	v_pk_fma_f32 v[34:35], v[26:27], v[52:53], v[34:35]
	v_mul_f32_e32 v54, v32, v32
	v_pk_add_f32 v[52:53], v[72:73], v[72:73] op_sel:[0,1] op_sel_hi:[1,0]
	v_pk_mul_f32 v[74:75], v[58:59], v[74:75] op_sel_hi:[0,1]
	v_mul_f32_e32 v58, v33, v33
	v_mov_b32_e32 v53, v54
	v_pk_add_f32 v[54:55], v[56:57], v[56:57] op_sel:[0,1] op_sel_hi:[1,0]
	v_pk_fma_f32 v[36:37], v[16:17], v[74:75], v[36:37]
	v_mov_b32_e32 v55, v58
	v_pk_add_f32 v[52:53], v[52:53], v[54:55]
	v_mul_f32_e32 v54, v37, v37
	v_mul_f32_e32 v56, v39, v39
	v_mul_f32_e32 v59, v34, v34
	v_mul_f32_e32 v71, v35, v35
	v_pk_fma_f32 v[54:55], v[36:37], v[36:37], v[54:55] op_sel_hi:[1,1,0]
	v_pk_fma_f32 v[56:57], v[38:39], v[38:39], v[56:57] op_sel_hi:[1,1,0]
	v_mov_b32_e32 v55, v59
	v_mov_b32_e32 v57, v71
	v_pk_add_f32 v[54:55], v[54:55], v[56:57]
	s_nop 0
	v_pk_add_f32 v[52:53], v[52:53], v[54:55]
	s_nop 0
	v_add_f32_e32 v52, v52, v53
	ds_bpermute_b32 v53, v64, v52
	s_waitcnt lgkmcnt(0)
	v_add_f32_e32 v52, v52, v53
	ds_bpermute_b32 v53, v65, v52
	s_waitcnt lgkmcnt(0)
	v_add_f32_e32 v52, v52, v53
	ds_bpermute_b32 v53, v66, v52
	s_waitcnt lgkmcnt(0)
	v_add_f32_e32 v52, v52, v53
	ds_bpermute_b32 v53, v67, v52
	s_waitcnt lgkmcnt(0)
	v_add_f32_e32 v52, v52, v53
	ds_bpermute_b32 v53, v68, v52
	s_waitcnt lgkmcnt(0)
	v_add_f32_e32 v52, v52, v53
	ds_bpermute_b32 v53, v69, v52
	s_waitcnt lgkmcnt(0)
	v_add_f32_e32 v52, v52, v53
	v_fmamk_f32 v52, v52, 0x3a800000, v70
	v_mul_f32_e32 v53, 0x4b800000, v52
	v_cmp_gt_f32_e32 vcc, s25, v52
	s_nop 1
	v_cndmask_b32_e32 v52, v52, v53, vcc
	v_rsq_f32_e32 v52, v52
	s_nop 0
	v_mul_f32_e32 v53, 0x45800000, v52
	v_cndmask_b32_e32 v52, v52, v53, vcc
	v_add_co_u32_e32 v54, vcc, s27, v62
	s_nop 1
	v_addc_co_u32_e32 v55, vcc, 0, v63, vcc
	s_nop 1
	v_pk_mul_f32 v[44:45], v[44:45], v[52:53] op_sel_hi:[1,0]
	v_pk_mul_f32 v[46:47], v[46:47], v[52:53] op_sel_hi:[1,0]
	v_pk_mul_f32 v[44:45], v[4:5], v[44:45]
	v_pk_mul_f32 v[46:47], v[6:7], v[46:47]
	v_cvt_pk_bf16_f32 v44, v44, v45
	v_cvt_pk_bf16_f32 v45, v46, v47
	global_store_dwordx2 v[60:61], v[44:45], off offset:2048
	s_nop 1
	v_pk_mul_f32 v[40:41], v[40:41], v[52:53] op_sel_hi:[1,0]
	v_pk_mul_f32 v[42:43], v[42:43], v[52:53] op_sel_hi:[1,0]
	v_pk_mul_f32 v[40:41], v[12:13], v[40:41]
	v_pk_mul_f32 v[42:43], v[14:15], v[42:43]
	v_cvt_pk_bf16_f32 v40, v40, v41
	v_cvt_pk_bf16_f32 v41, v42, v43
	global_store_dwordx2 v[60:61], v[40:41], off offset:2560
	s_nop 1
	v_pk_mul_f32 v[36:37], v[36:37], v[52:53] op_sel_hi:[1,0]
	v_pk_mul_f32 v[38:39], v[38:39], v[52:53] op_sel_hi:[1,0]
	v_pk_mul_f32 v[36:37], v[20:21], v[36:37]
	v_pk_mul_f32 v[38:39], v[22:23], v[38:39]
	v_cvt_pk_bf16_f32 v36, v36, v37
	v_cvt_pk_bf16_f32 v37, v38, v39
	global_store_dwordx2 v[60:61], v[36:37], off offset:3072
	s_nop 1
	v_pk_mul_f32 v[32:33], v[32:33], v[52:53] op_sel_hi:[1,0]
	v_pk_mul_f32 v[34:35], v[34:35], v[52:53] op_sel_hi:[1,0]
	v_pk_mul_f32 v[32:33], v[28:29], v[32:33]
	v_pk_mul_f32 v[34:35], v[30:31], v[34:35]
	v_cvt_pk_bf16_f32 v32, v32, v33
	v_cvt_pk_bf16_f32 v33, v34, v35
	global_store_dwordx2 v[60:61], v[32:33], off offset:3584
	s_branch .LBB0_1039

; __device__ __forceinline__ f32x4 up4(u32x2 w) { return (f32x4){bf_lo(w.x), bf_hi(w.x), bf_lo(w.y), bf_hi(w.y)}; }
; __device__ __forceinline__ void row_pass1(const Args& a, int row_lo, int row_hi, int gw, int NGW, int lane) {
;     ...
;         for (int r = 0; r < 2; ++r) { const int row = r0 + r; if (row >= row_hi) break;
;             const float rstd = rsqrtf(rs[r] * (1.f / DM) + EPS); f32x4 v[4]; float s = 0.f;
; #pragma unroll
;             for (int j = 0; j < 4; ++j) { v[j] = xv[r][j] + up4(yv[r][j]) * rstd * gp[j]; s += (v[j][0] * v[j][0] + v[j][1] * v[j][1]) + (v[j][2] * v[j][2] + v[j][3] * v[j][3]); }
; template <bool DRYR = false>
; __device__ __forceinline__ void row_pass2(const Args& a, int row_lo, int row_hi, int gw, int NGW, int lane) {
;     ...
;     for (int r0 = row_lo + 2 * gw; r0 < row_hi; r0 += 2 * NGW) {
;         f32x4 xv[2][4]; u32x2 fv[2][4]; float rs[2];
; #pragma unroll
;         for (int r = 0; r < 2; ++r) { const int row = (r0 + r < row_hi) ? r0 + r : r0; rs[r] = rss[row];
;             const f32x4* xo = (const f32x4*)(XO + (size_t)row * DM) + lane; const u32x2* fr = (const u32x2*)(F + (size_t)row * DM) + lane;
; #pragma unroll
;             for (int j = 0; j < 4; ++j) { xv[r][j] = xo[64 * j]; fv[r][j] = fr[64 * j]; } }
; #pragma unroll
;         for (int r = 0; r < 2; ++r) { const int row = r0 + r; if (row >= row_hi) break;
;             const float rstd = rsqrtf(rs[r] * (1.f / DM) + EPS); f32x4* xo = (f32x4*)(XO + (size_t)row * DM) + lane;
; #pragma unroll
;             for (int j = 0; j < 4; ++j) { const f32x4 o = xv[r][j] + up4(fv[r][j]) * rstd * gp[j]; if (!DRYR || o[0] == 123.456f) xo[64 * j] = o; } }
.LBB0_1413:
	s_and_b64 vcc, exec, s[10:11]
	s_cbranch_vccz .LBB0_1419
	s_lshl_b32 s0, s81, 1
	s_addk_i32 s0, 0xfe00
	s_cmpk_gt_i32 s0, 0x3fff
	s_cbranch_scc1 .LBB0_1419
	s_waitcnt vmcnt(0)
	v_mov_b32_e32 v145, 0
	v_readlane_b32 s20, v252, 1
	v_readlane_b32 s21, v252, 2
	v_readlane_b32 s14, v252, 13
	v_readlane_b32 s15, v252, 14
	v_lshlrev_b32_e32 v146, 3, v176
	v_add_u32_e32 v147, 0x1000, v144
	v_mov_b32_e32 v116, 0x358637bd
	s_lshl_b32 s1, s58, 4
	s_add_i32 s4, s1, 0xfffffe00
	s_ashr_i32 s1, s0, 31
	s_lshl_b64 s[10:11], s[0:1], 12
	global_load_dwordx4 v[84:87], v144, s[14:15]
	global_load_dwordx4 v[88:91], v144, s[14:15] offset:1024
	global_load_dwordx4 v[92:95], v144, s[14:15] offset:2048
	global_load_dwordx4 v[96:99], v144, s[14:15] offset:3072
	s_add_u32 s20, s20, s10
	s_addc_u32 s21, s21, s11
	s_add_u32 s22, s52, s10
	s_addc_u32 s23, s53, s11
	s_lshl_b64 s[10:11], s[0:1], 11
	s_add_u32 s24, s54, s10
	s_addc_u32 s25, s55, s11
	s_add_u32 s26, s24, 0xbc00000
	s_addc_u32 s27, s25, 0
	s_add_u32 s24, s24, 0xde00000
	s_addc_u32 s25, s25, 0
	s_lshl_b64 s[10:11], s[0:1], 2
	s_add_u32 s16, s54, s10
	s_addc_u32 s17, s55, s11
	s_add_u32 s18, s16, 0x2291000
	s_addc_u32 s19, s17, 0
	s_add_u32 s16, s16, 0x2280000
	s_addc_u32 s17, s17, 0
	s_lshl_b32 s98, s4, 12
	s_lshl_b32 s99, s4, 11
	s_lshl_b32 s100, s4, 2
	s_mov_b32 s3, 0x800000
.Lxo_loop:
	global_load_dwordx2 v[80:81], v145, s[16:17]
	global_load_dwordx2 v[82:83], v145, s[18:19]
	global_load_dwordx2 v[48:49], v146, s[24:25] nt
	global_load_dwordx2 v[50:51], v146, s[24:25] offset:512 nt
	global_load_dwordx2 v[52:53], v146, s[24:25] offset:1024 nt
	global_load_dwordx2 v[54:55], v146, s[24:25] offset:1536 nt
	global_load_dwordx4 v[16:19], v144, s[20:21] nt
	global_load_dwordx4 v[20:23], v144, s[20:21] offset:1024 nt
	global_load_dwordx4 v[24:27], v144, s[20:21] offset:2048 nt
	global_load_dwordx4 v[28:31], v144, s[20:21] offset:3072 nt
	global_load_dwordx2 v[64:65], v146, s[26:27] nt
	global_load_dwordx2 v[66:67], v146, s[26:27] offset:512 nt
	global_load_dwordx2 v[68:69], v146, s[26:27] offset:1024 nt
	global_load_dwordx2 v[70:71], v146, s[26:27] offset:1536 nt
	global_load_dwordx2 v[56:57], v146, s[24:25] offset:2048 nt
	global_load_dwordx2 v[58:59], v146, s[24:25] offset:2560 nt
	global_load_dwordx2 v[60:61], v146, s[24:25] offset:3072 nt
	global_load_dwordx2 v[62:63], v146, s[24:25] offset:3584 nt
	global_load_dwordx4 v[32:35], v147, s[20:21] nt
	global_load_dwordx4 v[36:39], v147, s[20:21] offset:1024 nt
	global_load_dwordx4 v[40:43], v147, s[20:21] offset:2048 nt
	global_load_dwordx4 v[44:47], v147, s[20:21] offset:3072 nt
	global_load_dwordx2 v[72:73], v146, s[26:27] offset:2048 nt
	global_load_dwordx2 v[74:75], v146, s[26:27] offset:2560 nt
	global_load_dwordx2 v[76:77], v146, s[26:27] offset:3072 nt
	global_load_dwordx2 v[78:79], v146, s[26:27] offset:3584 nt
	s_waitcnt vmcnt(12)
	v_fmamk_f32 v104, v80, 0x3a800000, v116
	v_mul_f32_e32 v105, 0x4b800000, v104
	v_cmp_gt_f32_e32 vcc, s3, v104
	s_nop 1
	v_cndmask_b32_e32 v104, v104, v105, vcc
	v_rsq_f32_e32 v104, v104
	s_nop 0
	v_mul_f32_e32 v105, 0x45800000, v104
	v_cndmask_b32_e32 v104, v104, v105, vcc
	v_fmamk_f32 v106, v82, 0x3a800000, v116
	v_mul_f32_e32 v107, 0x4b800000, v106
	v_cmp_gt_f32_e32 vcc, s3, v106
	s_nop 1
	v_cndmask_b32_e32 v106, v106, v107, vcc
	v_rsq_f32_e32 v106, v106
	s_nop 0
	v_mul_f32_e32 v107, 0x45800000, v106
	v_cndmask_b32_e32 v106, v106, v107, vcc
	v_lshlrev_b32_e32 v120, 16, v48
	v_and_b32_e32 v121, 0xffff0000, v48
	v_lshlrev_b32_e32 v122, 16, v49
	v_and_b32_e32 v123, 0xffff0000, v49
	v_lshlrev_b32_e32 v150, 16, v64
	v_and_b32_e32 v151, 0xffff0000, v64
	v_lshlrev_b32_e32 v152, 16, v65
	v_and_b32_e32 v153, 0xffff0000, v65
	v_pk_mul_f32 v[120:121], v[104:105], v[120:121] op_sel_hi:[0,1]
	v_pk_mul_f32 v[122:123], v[104:105], v[122:123] op_sel_hi:[0,1]
	v_pk_mul_f32 v[150:151], v[106:107], v[150:151] op_sel_hi:[0,1]
	v_pk_mul_f32 v[152:153], v[106:107], v[152:153] op_sel_hi:[0,1]
	v_pk_fma_f32 v[16:17], v[84:85], v[120:121], v[16:17]
	v_pk_fma_f32 v[18:19], v[86:87], v[122:123], v[18:19]
	v_pk_fma_f32 v[16:17], v[0:1], v[150:151], v[16:17]
	v_pk_fma_f32 v[18:19], v[2:3], v[152:153], v[18:19]
	v_lshlrev_b32_e32 v124, 16, v50
	v_and_b32_e32 v125, 0xffff0000, v50
	v_lshlrev_b32_e32 v126, 16, v51
	v_and_b32_e32 v127, 0xffff0000, v51
	v_lshlrev_b32_e32 v154, 16, v66
	v_and_b32_e32 v155, 0xffff0000, v66
	v_lshlrev_b32_e32 v156, 16, v67
	v_and_b32_e32 v157, 0xffff0000, v67
	v_pk_mul_f32 v[124:125], v[104:105], v[124:125] op_sel_hi:[0,1]
	v_pk_mul_f32 v[126:127], v[104:105], v[126:127] op_sel_hi:[0,1]
	v_pk_mul_f32 v[154:155], v[106:107], v[154:155] op_sel_hi:[0,1]
	v_pk_mul_f32 v[156:157], v[106:107], v[156:157] op_sel_hi:[0,1]
	v_pk_fma_f32 v[20:21], v[88:89], v[124:125], v[20:21]
	v_pk_fma_f32 v[22:23], v[90:91], v[126:127], v[22:23]
	v_pk_fma_f32 v[20:21], v[4:5], v[154:155], v[20:21]
	v_pk_fma_f32 v[22:23], v[6:7], v[156:157], v[22:23]
	v_lshlrev_b32_e32 v128, 16, v52
	v_and_b32_e32 v129, 0xffff0000, v52
	v_lshlrev_b32_e32 v130, 16, v53
	v_and_b32_e32 v131, 0xffff0000, v53
	v_lshlrev_b32_e32 v158, 16, v68
	v_and_b32_e32 v159, 0xffff0000, v68
	v_lshlrev_b32_e32 v160, 16, v69
	v_and_b32_e32 v161, 0xffff0000, v69
	v_pk_mul_f32 v[128:129], v[104:105], v[128:129] op_sel_hi:[0,1]
	v_pk_mul_f32 v[130:131], v[104:105], v[130:131] op_sel_hi:[0,1]
	v_pk_mul_f32 v[158:159], v[106:107], v[158:159] op_sel_hi:[0,1]
	v_pk_mul_f32 v[160:161], v[106:107], v[160:161] op_sel_hi:[0,1]
	v_pk_fma_f32 v[24:25], v[92:93], v[128:129], v[24:25]
	v_pk_fma_f32 v[26:27], v[94:95], v[130:131], v[26:27]
	v_pk_fma_f32 v[24:25], v[8:9], v[158:159], v[24:25]
	v_pk_fma_f32 v[26:27], v[10:11], v[160:161], v[26:27]
	v_lshlrev_b32_e32 v132, 16, v54
	v_and_b32_e32 v133, 0xffff0000, v54
	v_lshlrev_b32_e32 v134, 16, v55
	v_and_b32_e32 v135, 0xffff0000, v55
	v_lshlrev_b32_e32 v162, 16, v70
	v_and_b32_e32 v163, 0xffff0000, v70
	v_lshlrev_b32_e32 v164, 16, v71
	v_and_b32_e32 v165, 0xffff0000, v71
	v_pk_mul_f32 v[132:133], v[104:105], v[132:133] op_sel_hi:[0,1]
	v_pk_mul_f32 v[134:135], v[104:105], v[134:135] op_sel_hi:[0,1]
	v_pk_mul_f32 v[162:163], v[106:107], v[162:163] op_sel_hi:[0,1]
	v_pk_mul_f32 v[164:165], v[106:107], v[164:165] op_sel_hi:[0,1]
	v_pk_fma_f32 v[28:29], v[96:97], v[132:133], v[28:29]
	v_pk_fma_f32 v[30:31], v[98:99], v[134:135], v[30:31]
	v_pk_fma_f32 v[28:29], v[12:13], v[162:163], v[28:29]
	v_pk_fma_f32 v[30:31], v[14:15], v[164:165], v[30:31]
	global_store_dwordx4 v144, v[16:19], s[22:23] nt
	global_store_dwordx4 v144, v[20:23], s[22:23] offset:1024 nt
	global_store_dwordx4 v144, v[24:27], s[22:23] offset:2048 nt
	global_store_dwordx4 v144, v[28:31], s[22:23] offset:3072 nt
	s_waitcnt vmcnt(4)
; __device__ __forceinline__ f32x4 up4(u32x2 w) { return (f32x4){bf_lo(w.x), bf_hi(w.x), bf_lo(w.y), bf_hi(w.y)}; }
; template <bool DRYR = false>
; __device__ __forceinline__ void row_pass2(const Args& a, int row_lo, int row_hi, int gw, int NGW, int lane) {
;     ...
;         for (int r = 0; r < 2; ++r) { const int row = r0 + r; if (row >= row_hi) break;
;             const float rstd = rsqrtf(rs[r] * (1.f / DM) + EPS); f32x4* xo = (f32x4*)(XO + (size_t)row * DM) + lane;
; #pragma unroll
;             for (int j = 0; j < 4; ++j) { const f32x4 o = xv[r][j] + up4(fv[r][j]) * rstd * gp[j]; if (!DRYR || o[0] == 123.456f) xo[64 * j] = o; } }
	v_fmamk_f32 v104, v81, 0x3a800000, v116
	v_mul_f32_e32 v105, 0x4b800000, v104
	v_cmp_gt_f32_e32 vcc, s3, v104
	s_nop 1
	v_cndmask_b32_e32 v104, v104, v105, vcc
	v_rsq_f32_e32 v104, v104
	s_nop 0
	v_mul_f32_e32 v105, 0x45800000, v104
	v_cndmask_b32_e32 v104, v104, v105, vcc
	v_fmamk_f32 v106, v83, 0x3a800000, v116
	v_mul_f32_e32 v107, 0x4b800000, v106
	v_cmp_gt_f32_e32 vcc, s3, v106
	s_nop 1
	v_cndmask_b32_e32 v106, v106, v107, vcc
	v_rsq_f32_e32 v106, v106
	s_nop 0
	v_mul_f32_e32 v107, 0x45800000, v106
	v_cndmask_b32_e32 v106, v106, v107, vcc
	v_lshlrev_b32_e32 v120, 16, v56
	v_and_b32_e32 v121, 0xffff0000, v56
	v_lshlrev_b32_e32 v122, 16, v57
	v_and_b32_e32 v123, 0xffff0000, v57
	v_lshlrev_b32_e32 v150, 16, v72
	v_and_b32_e32 v151, 0xffff0000, v72
	v_lshlrev_b32_e32 v152, 16, v73
	v_and_b32_e32 v153, 0xffff0000, v73
	v_pk_mul_f32 v[120:121], v[104:105], v[120:121] op_sel_hi:[0,1]
	v_pk_mul_f32 v[122:123], v[104:105], v[122:123] op_sel_hi:[0,1]
	v_pk_mul_f32 v[150:151], v[106:107], v[150:151] op_sel_hi:[0,1]
	v_pk_mul_f32 v[152:153], v[106:107], v[152:153] op_sel_hi:[0,1]
	v_pk_fma_f32 v[32:33], v[84:85], v[120:121], v[32:33]
	v_pk_fma_f32 v[34:35], v[86:87], v[122:123], v[34:35]
	v_pk_fma_f32 v[32:33], v[0:1], v[150:151], v[32:33]
	v_pk_fma_f32 v[34:35], v[2:3], v[152:153], v[34:35]
	v_lshlrev_b32_e32 v124, 16, v58
	v_and_b32_e32 v125, 0xffff0000, v58
	v_lshlrev_b32_e32 v126, 16, v59
	v_and_b32_e32 v127, 0xffff0000, v59
	v_lshlrev_b32_e32 v154, 16, v74
	v_and_b32_e32 v155, 0xffff0000, v74
	v_lshlrev_b32_e32 v156, 16, v75
	v_and_b32_e32 v157, 0xffff0000, v75
	v_pk_mul_f32 v[124:125], v[104:105], v[124:125] op_sel_hi:[0,1]
	v_pk_mul_f32 v[126:127], v[104:105], v[126:127] op_sel_hi:[0,1]
	v_pk_mul_f32 v[154:155], v[106:107], v[154:155] op_sel_hi:[0,1]
	v_pk_mul_f32 v[156:157], v[106:107], v[156:157] op_sel_hi:[0,1]
	v_pk_fma_f32 v[36:37], v[88:89], v[124:125], v[36:37]
	v_pk_fma_f32 v[38:39], v[90:91], v[126:127], v[38:39]
	v_pk_fma_f32 v[36:37], v[4:5], v[154:155], v[36:37]
	v_pk_fma_f32 v[38:39], v[6:7], v[156:157], v[38:39]
	v_lshlrev_b32_e32 v128, 16, v60
	v_and_b32_e32 v129, 0xffff0000, v60
	v_lshlrev_b32_e32 v130, 16, v61
	v_and_b32_e32 v131, 0xffff0000, v61
	v_lshlrev_b32_e32 v158, 16, v76
	v_and_b32_e32 v159, 0xffff0000, v76
	v_lshlrev_b32_e32 v160, 16, v77
	v_and_b32_e32 v161, 0xffff0000, v77
	v_pk_mul_f32 v[128:129], v[104:105], v[128:129] op_sel_hi:[0,1]
	v_pk_mul_f32 v[130:131], v[104:105], v[130:131] op_sel_hi:[0,1]
	v_pk_mul_f32 v[158:159], v[106:107], v[158:159] op_sel_hi:[0,1]
	v_pk_mul_f32 v[160:161], v[106:107], v[160:161] op_sel_hi:[0,1]
	v_pk_fma_f32 v[40:41], v[92:93], v[128:129], v[40:41]
	v_pk_fma_f32 v[42:43], v[94:95], v[130:131], v[42:43]
	v_pk_fma_f32 v[40:41], v[8:9], v[158:159], v[40:41]
	v_pk_fma_f32 v[42:43], v[10:11], v[160:161], v[42:43]
	v_lshlrev_b32_e32 v132, 16, v62
	v_and_b32_e32 v133, 0xffff0000, v62
	v_lshlrev_b32_e32 v134, 16, v63
	v_and_b32_e32 v135, 0xffff0000, v63
	v_lshlrev_b32_e32 v162, 16, v78
	v_and_b32_e32 v163, 0xffff0000, v78
	v_lshlrev_b32_e32 v164, 16, v79
	v_and_b32_e32 v165, 0xffff0000, v79
	v_pk_mul_f32 v[132:133], v[104:105], v[132:133] op_sel_hi:[0,1]
	v_pk_mul_f32 v[134:135], v[104:105], v[134:135] op_sel_hi:[0,1]
	v_pk_mul_f32 v[162:163], v[106:107], v[162:163] op_sel_hi:[0,1]
	v_pk_mul_f32 v[164:165], v[106:107], v[164:165] op_sel_hi:[0,1]
	v_pk_fma_f32 v[44:45], v[96:97], v[132:133], v[44:45]
	v_pk_fma_f32 v[46:47], v[98:99], v[134:135], v[46:47]
	v_pk_fma_f32 v[44:45], v[12:13], v[162:163], v[44:45]
	v_pk_fma_f32 v[46:47], v[14:15], v[164:165], v[46:47]
	global_store_dwordx4 v147, v[32:35], s[22:23] nt
	global_store_dwordx4 v147, v[36:39], s[22:23] offset:1024 nt
	global_store_dwordx4 v147, v[40:43], s[22:23] offset:2048 nt
	global_store_dwordx4 v147, v[44:47], s[22:23] offset:3072 nt
	s_add_i32 s0, s0, s4
	s_add_u32 s20, s20, s98
	s_addc_u32 s21, s21, 0
	s_add_u32 s22, s22, s98
	s_addc_u32 s23, s23, 0
	s_add_u32 s24, s24, s99
	s_addc_u32 s25, s25, 0
	s_add_u32 s26, s26, s99
	s_addc_u32 s27, s27, 0
	s_add_u32 s16, s16, s100
	s_addc_u32 s17, s17, 0
	s_add_u32 s18, s18, s100
	s_addc_u32 s19, s19, 0
	s_cmpk_gt_i32 s0, 0x3fff
	s_cbranch_scc0 .Lxo_loop
